# FFN-up epilogue re-emitted batched across the 8 elements of a row group (same ops, packed f32 mul/add, no s_nop chains)
# baseline (speedup 1.0000x reference)
; DI unsigned cvt_pk_bf16(float lo, float hi) { unsigned r; asm volatile("v_cvt_pk_bf16_f32 %0, %1, %2" : "=v"(r) : "v"(lo), "v"(hi)); return r; }
; DI float sigm(float x) { return __builtin_amdgcn_rcpf(1.f + __expf(-x)); }
;     DI void operator()(const AccT& acc, const pg8::Unit& u, int wr, int wc, int fr, int fq) const {
;         const int row0 = u.pm * 256 + wr * 64 + fr, ff0 = u.pn * 128 + wc * 32 + 8 * fq;
;         float rsv[8];
; #pragma unroll
;         for (int k = 0; k < 8; ++k) rsv[k] = (float)rowss[row0 + (k >> 2) * 128 + (k & 3) * 16] * RS_INV;
; #pragma unroll
;         for (int ai = 0; ai < 2; ++ai)
; #pragma unroll
;             for (int m = 0; m < 4; ++m) {
;                 const int row = row0 + ai * 128 + m * 16;
;                 const float rs = rsqrtf(rsv[ai * 4 + m] * (1.f / DM) + 1e-6f);
;                 float o[8];
; #pragma unroll
;                 for (int n = 0; n < 2; ++n) {
;                     const f32x4 gv = acc[ai][0][m][n] * rs, uv = acc[ai][1][m][n] * rs;
; #pragma unroll
;                     for (int j = 0; j < 4; ++j) o[4 * n + j] = gv[j] * sigm(gv[j]) * uv[j];
;                 }
;                 u32x4 w; w.x = cvt_pk_bf16(o[0], o[1]); w.y = cvt_pk_bf16(o[2], o[3]); w.z = cvt_pk_bf16(o[4], o[5]); w.w = cvt_pk_bf16(o[6], o[7]);
;                 *(u32x4*)(ACT + (size_t)row * DFF + ff0) = w;
.LBB0_27:
	v_lshl_add_u32 v140, s12, 8, v142
	v_ashrrev_i32_e32 v141, 31, v140
	v_lshl_add_u64 v[152:153], v[140:141], 2, s[44:45]
	global_load_dword v154, v[152:153], off
	global_load_dword v155, v[152:153], off offset:64
	global_load_dword v156, v[152:153], off offset:128
	global_load_dword v157, v[152:153], off offset:192
	global_load_dword v158, v[152:153], off offset:512
	global_load_dword v159, v[152:153], off offset:576
	global_load_dword v160, v[152:153], off offset:640
	global_load_dword v161, v[152:153], off offset:704
	v_lshl_or_b32 v198, s4, 7, v144
	v_ashrrev_i32_e32 v199, 31, v198
	v_lshlrev_b64 v[198:199], 1, v[198:199]
	v_mov_b64_e32 v[196:197], s[52:53]
	v_mov_b32_e32 v168, 1.0
	v_mov_b32_e32 v170, 0xbfb8aa3b
	v_mov_b32_e32 v172, 0x3a000000
	s_waitcnt vmcnt(0)
	v_cvt_f32_u32_e32 v154, v154
	v_cvt_f32_u32_e32 v155, v155
	v_cvt_f32_u32_e32 v156, v156
	v_cvt_f32_u32_e32 v157, v157
	v_cvt_f32_u32_e32 v158, v158
	v_cvt_f32_u32_e32 v159, v159
	v_cvt_f32_u32_e32 v160, v160
	v_cvt_f32_u32_e32 v161, v161
	v_mul_f32_e32 v154, s24, v154
	v_mul_f32_e32 v155, s24, v155
	v_mul_f32_e32 v156, s24, v156
	v_mul_f32_e32 v157, s24, v157
	v_mul_f32_e32 v158, s24, v158
	v_mul_f32_e32 v159, s24, v159
	v_mul_f32_e32 v160, s24, v160
	v_mul_f32_e32 v161, s24, v161
	v_fmaak_f32 v154, v172, v154, 0x358637bd
	v_fmaak_f32 v155, v172, v155, 0x358637bd
	v_fmaak_f32 v156, v172, v156, 0x358637bd
	v_fmaak_f32 v157, v172, v157, 0x358637bd
	v_fmaak_f32 v158, v172, v158, 0x358637bd
	v_fmaak_f32 v159, v172, v159, 0x358637bd
	v_fmaak_f32 v160, v172, v160, 0x358637bd
	v_fmaak_f32 v161, v172, v161, 0x358637bd
	v_rsq_f32_e32 v154, v154
	v_rsq_f32_e32 v155, v155
	v_rsq_f32_e32 v156, v156
	v_rsq_f32_e32 v157, v157
	v_rsq_f32_e32 v158, v158
	v_rsq_f32_e32 v159, v159
	v_rsq_f32_e32 v160, v160
	v_rsq_f32_e32 v161, v161
	v_pk_mul_f32 v[118:119], v[118:119], v[154:155] op_sel_hi:[1,0]
	v_pk_mul_f32 v[120:121], v[120:121], v[154:155] op_sel_hi:[1,0]
	v_pk_mul_f32 v[114:115], v[114:115], v[154:155] op_sel_hi:[1,0]
	v_pk_mul_f32 v[116:117], v[116:117], v[154:155] op_sel_hi:[1,0]
	v_pk_mul_f32 v[126:127], v[126:127], v[154:155] op_sel_hi:[1,0]
	v_pk_mul_f32 v[128:129], v[128:129], v[154:155] op_sel_hi:[1,0]
	v_pk_mul_f32 v[122:123], v[122:123], v[154:155] op_sel_hi:[1,0]
	v_pk_mul_f32 v[124:125], v[124:125], v[154:155] op_sel_hi:[1,0]
	v_pk_mul_f32 v[186:187], v[118:119], v[170:171] op_sel_hi:[1,0]
	v_pk_mul_f32 v[188:189], v[120:121], v[170:171] op_sel_hi:[1,0]
	v_pk_mul_f32 v[190:191], v[114:115], v[170:171] op_sel_hi:[1,0]
	v_pk_mul_f32 v[192:193], v[116:117], v[170:171] op_sel_hi:[1,0]
	v_exp_f32_e32 v186, v186
	v_exp_f32_e32 v187, v187
	v_exp_f32_e32 v188, v188
	v_exp_f32_e32 v189, v189
	v_exp_f32_e32 v190, v190
	v_exp_f32_e32 v191, v191
	v_exp_f32_e32 v192, v192
	v_exp_f32_e32 v193, v193
	v_pk_add_f32 v[186:187], v[186:187], v[168:169] op_sel_hi:[1,0]
	v_pk_add_f32 v[188:189], v[188:189], v[168:169] op_sel_hi:[1,0]
	v_pk_add_f32 v[190:191], v[190:191], v[168:169] op_sel_hi:[1,0]
	v_pk_add_f32 v[192:193], v[192:193], v[168:169] op_sel_hi:[1,0]
	v_rcp_f32_e32 v186, v186
	v_rcp_f32_e32 v187, v187
	v_rcp_f32_e32 v188, v188
	v_rcp_f32_e32 v189, v189
	v_rcp_f32_e32 v190, v190
	v_rcp_f32_e32 v191, v191
	v_rcp_f32_e32 v192, v192
	v_rcp_f32_e32 v193, v193
	v_pk_mul_f32 v[118:119], v[118:119], v[186:187]
	v_pk_mul_f32 v[120:121], v[120:121], v[188:189]
	v_pk_mul_f32 v[114:115], v[114:115], v[190:191]
	v_pk_mul_f32 v[116:117], v[116:117], v[192:193]
	v_pk_mul_f32 v[126:127], v[126:127], v[118:119]
	v_pk_mul_f32 v[128:129], v[128:129], v[120:121]
	v_pk_mul_f32 v[122:123], v[122:123], v[114:115]
	v_pk_mul_f32 v[124:125], v[124:125], v[116:117]
	v_mad_i64_i32 v[194:195], s[42:43], v140, s31, v[196:197]
	v_lshl_add_u64 v[194:195], v[194:195], 0, v[198:199]
	v_cvt_pk_bf16_f32 v118, v126, v127
	v_cvt_pk_bf16_f32 v119, v128, v129
	v_cvt_pk_bf16_f32 v120, v122, v123
	v_cvt_pk_bf16_f32 v121, v124, v125
	global_store_dwordx4 v[194:195], v[118:121], off
	v_mov_b32_e32 v194, v155
	v_pk_mul_f32 v[110:111], v[110:111], v[194:195] op_sel_hi:[1,0]
	v_pk_mul_f32 v[112:113], v[112:113], v[194:195] op_sel_hi:[1,0]
	v_pk_mul_f32 v[102:103], v[102:103], v[194:195] op_sel_hi:[1,0]
	v_pk_mul_f32 v[104:105], v[104:105], v[194:195] op_sel_hi:[1,0]
	v_pk_mul_f32 v[106:107], v[106:107], v[194:195] op_sel_hi:[1,0]
	v_pk_mul_f32 v[108:109], v[108:109], v[194:195] op_sel_hi:[1,0]
	v_pk_mul_f32 v[98:99], v[98:99], v[194:195] op_sel_hi:[1,0]
	v_pk_mul_f32 v[100:101], v[100:101], v[194:195] op_sel_hi:[1,0]
	v_pk_mul_f32 v[186:187], v[110:111], v[170:171] op_sel_hi:[1,0]
	v_pk_mul_f32 v[188:189], v[112:113], v[170:171] op_sel_hi:[1,0]
	v_pk_mul_f32 v[190:191], v[102:103], v[170:171] op_sel_hi:[1,0]
	v_pk_mul_f32 v[192:193], v[104:105], v[170:171] op_sel_hi:[1,0]
	v_exp_f32_e32 v186, v186
	v_exp_f32_e32 v187, v187
	v_exp_f32_e32 v188, v188
	v_exp_f32_e32 v189, v189
	v_exp_f32_e32 v190, v190
	v_exp_f32_e32 v191, v191
	v_exp_f32_e32 v192, v192
	v_exp_f32_e32 v193, v193
	v_pk_add_f32 v[186:187], v[186:187], v[168:169] op_sel_hi:[1,0]
	v_pk_add_f32 v[188:189], v[188:189], v[168:169] op_sel_hi:[1,0]
	v_pk_add_f32 v[190:191], v[190:191], v[168:169] op_sel_hi:[1,0]
	v_pk_add_f32 v[192:193], v[192:193], v[168:169] op_sel_hi:[1,0]
	v_rcp_f32_e32 v186, v186
	v_rcp_f32_e32 v187, v187
	v_rcp_f32_e32 v188, v188
	v_rcp_f32_e32 v189, v189
	v_rcp_f32_e32 v190, v190
	v_rcp_f32_e32 v191, v191
	v_rcp_f32_e32 v192, v192
	v_rcp_f32_e32 v193, v193
	v_pk_mul_f32 v[110:111], v[110:111], v[186:187]
	v_pk_mul_f32 v[112:113], v[112:113], v[188:189]
	v_pk_mul_f32 v[102:103], v[102:103], v[190:191]
	v_pk_mul_f32 v[104:105], v[104:105], v[192:193]
; DI unsigned cvt_pk_bf16(float lo, float hi) { unsigned r; asm volatile("v_cvt_pk_bf16_f32 %0, %1, %2" : "=v"(r) : "v"(lo), "v"(hi)); return r; }
; DI float sigm(float x) { return __builtin_amdgcn_rcpf(1.f + __expf(-x)); }
;     DI void operator()(const AccT& acc, const pg8::Unit& u, int wr, int wc, int fr, int fq) const {
;     ...
;         for (int ai = 0; ai < 2; ++ai)
; #pragma unroll
;             for (int m = 0; m < 4; ++m) {
;                 const int row = row0 + ai * 128 + m * 16;
;                 const float rs = rsqrtf(rsv[ai * 4 + m] * (1.f / DM) + 1e-6f);
;                 float o[8];
; #pragma unroll
;                 for (int n = 0; n < 2; ++n) {
;                     const f32x4 gv = acc[ai][0][m][n] * rs, uv = acc[ai][1][m][n] * rs;
; #pragma unroll
;                     for (int j = 0; j < 4; ++j) o[4 * n + j] = gv[j] * sigm(gv[j]) * uv[j];
;                 }
;                 u32x4 w; w.x = cvt_pk_bf16(o[0], o[1]); w.y = cvt_pk_bf16(o[2], o[3]); w.z = cvt_pk_bf16(o[4], o[5]); w.w = cvt_pk_bf16(o[6], o[7]);
;                 *(u32x4*)(ACT + (size_t)row * DFF + ff0) = w;
	v_pk_mul_f32 v[106:107], v[106:107], v[110:111]
	v_pk_mul_f32 v[108:109], v[108:109], v[112:113]
	v_pk_mul_f32 v[98:99], v[98:99], v[102:103]
	v_pk_mul_f32 v[100:101], v[100:101], v[104:105]
	v_add_u32_e32 v194, 16, v140
	v_mad_i64_i32 v[194:195], s[42:43], v194, s31, v[196:197]
	v_lshl_add_u64 v[194:195], v[194:195], 0, v[198:199]
	v_cvt_pk_bf16_f32 v110, v106, v107
	v_cvt_pk_bf16_f32 v111, v108, v109
	v_cvt_pk_bf16_f32 v112, v98, v99
	v_cvt_pk_bf16_f32 v113, v100, v101
	global_store_dwordx4 v[194:195], v[110:113], off
	v_pk_mul_f32 v[86:87], v[86:87], v[156:157] op_sel_hi:[1,0]
	v_pk_mul_f32 v[88:89], v[88:89], v[156:157] op_sel_hi:[1,0]
	v_pk_mul_f32 v[82:83], v[82:83], v[156:157] op_sel_hi:[1,0]
	v_pk_mul_f32 v[84:85], v[84:85], v[156:157] op_sel_hi:[1,0]
	v_pk_mul_f32 v[94:95], v[94:95], v[156:157] op_sel_hi:[1,0]
	v_pk_mul_f32 v[96:97], v[96:97], v[156:157] op_sel_hi:[1,0]
	v_pk_mul_f32 v[90:91], v[90:91], v[156:157] op_sel_hi:[1,0]
	v_pk_mul_f32 v[92:93], v[92:93], v[156:157] op_sel_hi:[1,0]
	v_pk_mul_f32 v[186:187], v[86:87], v[170:171] op_sel_hi:[1,0]
	v_pk_mul_f32 v[188:189], v[88:89], v[170:171] op_sel_hi:[1,0]
	v_pk_mul_f32 v[190:191], v[82:83], v[170:171] op_sel_hi:[1,0]
	v_pk_mul_f32 v[192:193], v[84:85], v[170:171] op_sel_hi:[1,0]
	v_exp_f32_e32 v186, v186
	v_exp_f32_e32 v187, v187
	v_exp_f32_e32 v188, v188
	v_exp_f32_e32 v189, v189
	v_exp_f32_e32 v190, v190
	v_exp_f32_e32 v191, v191
	v_exp_f32_e32 v192, v192
	v_exp_f32_e32 v193, v193
	v_pk_add_f32 v[186:187], v[186:187], v[168:169] op_sel_hi:[1,0]
	v_pk_add_f32 v[188:189], v[188:189], v[168:169] op_sel_hi:[1,0]
	v_pk_add_f32 v[190:191], v[190:191], v[168:169] op_sel_hi:[1,0]
	v_pk_add_f32 v[192:193], v[192:193], v[168:169] op_sel_hi:[1,0]
	v_rcp_f32_e32 v186, v186
	v_rcp_f32_e32 v187, v187
	v_rcp_f32_e32 v188, v188
	v_rcp_f32_e32 v189, v189
	v_rcp_f32_e32 v190, v190
	v_rcp_f32_e32 v191, v191
	v_rcp_f32_e32 v192, v192
	v_rcp_f32_e32 v193, v193
	v_pk_mul_f32 v[86:87], v[86:87], v[186:187]
	v_pk_mul_f32 v[88:89], v[88:89], v[188:189]
	v_pk_mul_f32 v[82:83], v[82:83], v[190:191]
	v_pk_mul_f32 v[84:85], v[84:85], v[192:193]
	v_pk_mul_f32 v[94:95], v[94:95], v[86:87]
	v_pk_mul_f32 v[96:97], v[96:97], v[88:89]
	v_pk_mul_f32 v[90:91], v[90:91], v[82:83]
	v_pk_mul_f32 v[92:93], v[92:93], v[84:85]
	v_add_u32_e32 v194, 32, v140
	v_mad_i64_i32 v[194:195], s[42:43], v194, s31, v[196:197]
	v_lshl_add_u64 v[194:195], v[194:195], 0, v[198:199]
	v_cvt_pk_bf16_f32 v86, v94, v95
	v_cvt_pk_bf16_f32 v87, v96, v97
	v_cvt_pk_bf16_f32 v88, v90, v91
	v_cvt_pk_bf16_f32 v89, v92, v93
	global_store_dwordx4 v[194:195], v[86:89], off
	v_mov_b32_e32 v194, v157
	v_pk_mul_f32 v[78:79], v[78:79], v[194:195] op_sel_hi:[1,0]
	v_pk_mul_f32 v[80:81], v[80:81], v[194:195] op_sel_hi:[1,0]
	v_pk_mul_f32 v[70:71], v[70:71], v[194:195] op_sel_hi:[1,0]
	v_pk_mul_f32 v[72:73], v[72:73], v[194:195] op_sel_hi:[1,0]
	v_pk_mul_f32 v[74:75], v[74:75], v[194:195] op_sel_hi:[1,0]
	v_pk_mul_f32 v[76:77], v[76:77], v[194:195] op_sel_hi:[1,0]
	v_pk_mul_f32 v[66:67], v[66:67], v[194:195] op_sel_hi:[1,0]
	v_pk_mul_f32 v[68:69], v[68:69], v[194:195] op_sel_hi:[1,0]
	v_pk_mul_f32 v[186:187], v[78:79], v[170:171] op_sel_hi:[1,0]
	v_pk_mul_f32 v[188:189], v[80:81], v[170:171] op_sel_hi:[1,0]
	v_pk_mul_f32 v[190:191], v[70:71], v[170:171] op_sel_hi:[1,0]
	v_pk_mul_f32 v[192:193], v[72:73], v[170:171] op_sel_hi:[1,0]
	v_exp_f32_e32 v186, v186
	v_exp_f32_e32 v187, v187
	v_exp_f32_e32 v188, v188
	v_exp_f32_e32 v189, v189
	v_exp_f32_e32 v190, v190
	v_exp_f32_e32 v191, v191
	v_exp_f32_e32 v192, v192
	v_exp_f32_e32 v193, v193
	v_pk_add_f32 v[186:187], v[186:187], v[168:169] op_sel_hi:[1,0]
	v_pk_add_f32 v[188:189], v[188:189], v[168:169] op_sel_hi:[1,0]
	v_pk_add_f32 v[190:191], v[190:191], v[168:169] op_sel_hi:[1,0]
	v_pk_add_f32 v[192:193], v[192:193], v[168:169] op_sel_hi:[1,0]
	v_rcp_f32_e32 v186, v186
	v_rcp_f32_e32 v187, v187
	v_rcp_f32_e32 v188, v188
	v_rcp_f32_e32 v189, v189
	v_rcp_f32_e32 v190, v190
	v_rcp_f32_e32 v191, v191
	v_rcp_f32_e32 v192, v192
	v_rcp_f32_e32 v193, v193
	v_pk_mul_f32 v[78:79], v[78:79], v[186:187]
	v_pk_mul_f32 v[80:81], v[80:81], v[188:189]
	v_pk_mul_f32 v[70:71], v[70:71], v[190:191]
	v_pk_mul_f32 v[72:73], v[72:73], v[192:193]
	v_pk_mul_f32 v[74:75], v[74:75], v[78:79]
	v_pk_mul_f32 v[76:77], v[76:77], v[80:81]
	v_pk_mul_f32 v[66:67], v[66:67], v[70:71]
	v_pk_mul_f32 v[68:69], v[68:69], v[72:73]
	v_add_u32_e32 v194, 48, v140
	v_mad_i64_i32 v[194:195], s[42:43], v194, s31, v[196:197]
	v_lshl_add_u64 v[194:195], v[194:195], 0, v[198:199]
	v_cvt_pk_bf16_f32 v78, v74, v75
	v_cvt_pk_bf16_f32 v79, v76, v77
	v_cvt_pk_bf16_f32 v80, v66, v67
	v_cvt_pk_bf16_f32 v81, v68, v69
	global_store_dwordx4 v[194:195], v[78:81], off
	v_pk_mul_f32 v[54:55], v[54:55], v[158:159] op_sel_hi:[1,0]
	v_pk_mul_f32 v[56:57], v[56:57], v[158:159] op_sel_hi:[1,0]
	v_pk_mul_f32 v[50:51], v[50:51], v[158:159] op_sel_hi:[1,0]
	v_pk_mul_f32 v[52:53], v[52:53], v[158:159] op_sel_hi:[1,0]
	v_pk_mul_f32 v[62:63], v[62:63], v[158:159] op_sel_hi:[1,0]
	v_pk_mul_f32 v[64:65], v[64:65], v[158:159] op_sel_hi:[1,0]
	v_pk_mul_f32 v[58:59], v[58:59], v[158:159] op_sel_hi:[1,0]
	v_pk_mul_f32 v[60:61], v[60:61], v[158:159] op_sel_hi:[1,0]
	v_pk_mul_f32 v[186:187], v[54:55], v[170:171] op_sel_hi:[1,0]
	v_pk_mul_f32 v[188:189], v[56:57], v[170:171] op_sel_hi:[1,0]
	v_pk_mul_f32 v[190:191], v[50:51], v[170:171] op_sel_hi:[1,0]
	v_pk_mul_f32 v[192:193], v[52:53], v[170:171] op_sel_hi:[1,0]
	v_exp_f32_e32 v186, v186
	v_exp_f32_e32 v187, v187
	v_exp_f32_e32 v188, v188
	v_exp_f32_e32 v189, v189
	v_exp_f32_e32 v190, v190
	v_exp_f32_e32 v191, v191
; DI unsigned cvt_pk_bf16(float lo, float hi) { unsigned r; asm volatile("v_cvt_pk_bf16_f32 %0, %1, %2" : "=v"(r) : "v"(lo), "v"(hi)); return r; }
; DI float sigm(float x) { return __builtin_amdgcn_rcpf(1.f + __expf(-x)); }
;     DI void operator()(const AccT& acc, const pg8::Unit& u, int wr, int wc, int fr, int fq) const {
;     ...
;         for (int ai = 0; ai < 2; ++ai)
; #pragma unroll
;             for (int m = 0; m < 4; ++m) {
;                 const int row = row0 + ai * 128 + m * 16;
;                 const float rs = rsqrtf(rsv[ai * 4 + m] * (1.f / DM) + 1e-6f);
;                 float o[8];
; #pragma unroll
;                 for (int n = 0; n < 2; ++n) {
;                     const f32x4 gv = acc[ai][0][m][n] * rs, uv = acc[ai][1][m][n] * rs;
; #pragma unroll
;                     for (int j = 0; j < 4; ++j) o[4 * n + j] = gv[j] * sigm(gv[j]) * uv[j];
;                 }
;                 u32x4 w; w.x = cvt_pk_bf16(o[0], o[1]); w.y = cvt_pk_bf16(o[2], o[3]); w.z = cvt_pk_bf16(o[4], o[5]); w.w = cvt_pk_bf16(o[6], o[7]);
;                 *(u32x4*)(ACT + (size_t)row * DFF + ff0) = w;
	v_exp_f32_e32 v192, v192
	v_exp_f32_e32 v193, v193
	v_pk_add_f32 v[186:187], v[186:187], v[168:169] op_sel_hi:[1,0]
	v_pk_add_f32 v[188:189], v[188:189], v[168:169] op_sel_hi:[1,0]
	v_pk_add_f32 v[190:191], v[190:191], v[168:169] op_sel_hi:[1,0]
	v_pk_add_f32 v[192:193], v[192:193], v[168:169] op_sel_hi:[1,0]
	v_rcp_f32_e32 v186, v186
	v_rcp_f32_e32 v187, v187
	v_rcp_f32_e32 v188, v188
	v_rcp_f32_e32 v189, v189
	v_rcp_f32_e32 v190, v190
	v_rcp_f32_e32 v191, v191
	v_rcp_f32_e32 v192, v192
	v_rcp_f32_e32 v193, v193
	v_pk_mul_f32 v[54:55], v[54:55], v[186:187]
	v_pk_mul_f32 v[56:57], v[56:57], v[188:189]
	v_pk_mul_f32 v[50:51], v[50:51], v[190:191]
	v_pk_mul_f32 v[52:53], v[52:53], v[192:193]
	v_pk_mul_f32 v[62:63], v[62:63], v[54:55]
	v_pk_mul_f32 v[64:65], v[64:65], v[56:57]
	v_pk_mul_f32 v[58:59], v[58:59], v[50:51]
	v_pk_mul_f32 v[60:61], v[60:61], v[52:53]
	v_add_u32_e32 v194, 128, v140
	v_mad_i64_i32 v[194:195], s[42:43], v194, s31, v[196:197]
	v_lshl_add_u64 v[194:195], v[194:195], 0, v[198:199]
	v_cvt_pk_bf16_f32 v54, v62, v63
	v_cvt_pk_bf16_f32 v55, v64, v65
	v_cvt_pk_bf16_f32 v56, v58, v59
	v_cvt_pk_bf16_f32 v57, v60, v61
	global_store_dwordx4 v[194:195], v[54:57], off
	v_mov_b32_e32 v194, v159
	v_pk_mul_f32 v[46:47], v[46:47], v[194:195] op_sel_hi:[1,0]
	v_pk_mul_f32 v[48:49], v[48:49], v[194:195] op_sel_hi:[1,0]
	v_pk_mul_f32 v[38:39], v[38:39], v[194:195] op_sel_hi:[1,0]
	v_pk_mul_f32 v[40:41], v[40:41], v[194:195] op_sel_hi:[1,0]
	v_pk_mul_f32 v[42:43], v[42:43], v[194:195] op_sel_hi:[1,0]
	v_pk_mul_f32 v[44:45], v[44:45], v[194:195] op_sel_hi:[1,0]
	v_pk_mul_f32 v[34:35], v[34:35], v[194:195] op_sel_hi:[1,0]
	v_pk_mul_f32 v[36:37], v[36:37], v[194:195] op_sel_hi:[1,0]
	v_pk_mul_f32 v[186:187], v[46:47], v[170:171] op_sel_hi:[1,0]
	v_pk_mul_f32 v[188:189], v[48:49], v[170:171] op_sel_hi:[1,0]
	v_pk_mul_f32 v[190:191], v[38:39], v[170:171] op_sel_hi:[1,0]
	v_pk_mul_f32 v[192:193], v[40:41], v[170:171] op_sel_hi:[1,0]
	v_exp_f32_e32 v186, v186
	v_exp_f32_e32 v187, v187
	v_exp_f32_e32 v188, v188
	v_exp_f32_e32 v189, v189
	v_exp_f32_e32 v190, v190
	v_exp_f32_e32 v191, v191
	v_exp_f32_e32 v192, v192
	v_exp_f32_e32 v193, v193
	v_pk_add_f32 v[186:187], v[186:187], v[168:169] op_sel_hi:[1,0]
	v_pk_add_f32 v[188:189], v[188:189], v[168:169] op_sel_hi:[1,0]
	v_pk_add_f32 v[190:191], v[190:191], v[168:169] op_sel_hi:[1,0]
	v_pk_add_f32 v[192:193], v[192:193], v[168:169] op_sel_hi:[1,0]
	v_rcp_f32_e32 v186, v186
	v_rcp_f32_e32 v187, v187
	v_rcp_f32_e32 v188, v188
	v_rcp_f32_e32 v189, v189
	v_rcp_f32_e32 v190, v190
	v_rcp_f32_e32 v191, v191
	v_rcp_f32_e32 v192, v192
	v_rcp_f32_e32 v193, v193
	v_pk_mul_f32 v[46:47], v[46:47], v[186:187]
	v_pk_mul_f32 v[48:49], v[48:49], v[188:189]
	v_pk_mul_f32 v[38:39], v[38:39], v[190:191]
	v_pk_mul_f32 v[40:41], v[40:41], v[192:193]
	v_pk_mul_f32 v[42:43], v[42:43], v[46:47]
	v_pk_mul_f32 v[44:45], v[44:45], v[48:49]
	v_pk_mul_f32 v[34:35], v[34:35], v[38:39]
	v_pk_mul_f32 v[36:37], v[36:37], v[40:41]
	v_add_u32_e32 v194, 144, v140
	v_mad_i64_i32 v[194:195], s[42:43], v194, s31, v[196:197]
	v_lshl_add_u64 v[194:195], v[194:195], 0, v[198:199]
	v_cvt_pk_bf16_f32 v46, v42, v43
	v_cvt_pk_bf16_f32 v47, v44, v45
	v_cvt_pk_bf16_f32 v48, v34, v35
	v_cvt_pk_bf16_f32 v49, v36, v37
	global_store_dwordx4 v[194:195], v[46:49], off
	v_pk_mul_f32 v[22:23], v[22:23], v[160:161] op_sel_hi:[1,0]
	v_pk_mul_f32 v[24:25], v[24:25], v[160:161] op_sel_hi:[1,0]
	v_pk_mul_f32 v[18:19], v[18:19], v[160:161] op_sel_hi:[1,0]
	v_pk_mul_f32 v[20:21], v[20:21], v[160:161] op_sel_hi:[1,0]
	v_pk_mul_f32 v[30:31], v[30:31], v[160:161] op_sel_hi:[1,0]
	v_pk_mul_f32 v[32:33], v[32:33], v[160:161] op_sel_hi:[1,0]
	v_pk_mul_f32 v[26:27], v[26:27], v[160:161] op_sel_hi:[1,0]
	v_pk_mul_f32 v[28:29], v[28:29], v[160:161] op_sel_hi:[1,0]
; DI unsigned cvt_pk_bf16(float lo, float hi) { unsigned r; asm volatile("v_cvt_pk_bf16_f32 %0, %1, %2" : "=v"(r) : "v"(lo), "v"(hi)); return r; }
; DI float sigm(float x) { return __builtin_amdgcn_rcpf(1.f + __expf(-x)); }
; #define PG8_BAR __builtin_amdgcn_s_barrier()
; template <class Epi, class Sched>
; __device__ __forceinline__ void gemm_phase(PG8_LAS unsigned char* lds, const Gemm g, const Sched& S, const Epi& E) {
;     ...
;         if (!has_next) break;
; #pragma unroll
;         for (int a = 0; a < 2; ++a)
; #pragma unroll
;             for (int b = 0; b < 2; ++b)
; #pragma unroll
;                 for (int m = 0; m < 4; ++m)
; #pragma unroll
;                     for (int n = 0; n < 2; ++n) acc[a][b][m][n] = (f32x4){0.f, 0.f, 0.f, 0.f};
;         cur = nxt; cA = nA; cB = nB; ++ui;
;         if (wr == 1) PG8_BAR;
;     DI void operator()(const AccT& acc, const pg8::Unit& u, int wr, int wc, int fr, int fq) const {
;     ...
;         for (int ai = 0; ai < 2; ++ai)
; #pragma unroll
;             for (int m = 0; m < 4; ++m) {
;                 const int row = row0 + ai * 128 + m * 16;
;                 const float rs = rsqrtf(rsv[ai * 4 + m] * (1.f / DM) + 1e-6f);
;                 float o[8];
; #pragma unroll
;                 for (int n = 0; n < 2; ++n) {
;                     const f32x4 gv = acc[ai][0][m][n] * rs, uv = acc[ai][1][m][n] * rs;
; #pragma unroll
;                     for (int j = 0; j < 4; ++j) o[4 * n + j] = gv[j] * sigm(gv[j]) * uv[j];
;                 }
;                 u32x4 w; w.x = cvt_pk_bf16(o[0], o[1]); w.y = cvt_pk_bf16(o[2], o[3]); w.z = cvt_pk_bf16(o[4], o[5]); w.w = cvt_pk_bf16(o[6], o[7]);
;                 *(u32x4*)(ACT + (size_t)row * DFF + ff0) = w;
	v_pk_mul_f32 v[186:187], v[22:23], v[170:171] op_sel_hi:[1,0]
	v_pk_mul_f32 v[188:189], v[24:25], v[170:171] op_sel_hi:[1,0]
	v_pk_mul_f32 v[190:191], v[18:19], v[170:171] op_sel_hi:[1,0]
	v_pk_mul_f32 v[192:193], v[20:21], v[170:171] op_sel_hi:[1,0]
	v_exp_f32_e32 v186, v186
	v_exp_f32_e32 v187, v187
	v_exp_f32_e32 v188, v188
	v_exp_f32_e32 v189, v189
	v_exp_f32_e32 v190, v190
	v_exp_f32_e32 v191, v191
	v_exp_f32_e32 v192, v192
	v_exp_f32_e32 v193, v193
	v_pk_add_f32 v[186:187], v[186:187], v[168:169] op_sel_hi:[1,0]
	v_pk_add_f32 v[188:189], v[188:189], v[168:169] op_sel_hi:[1,0]
	v_pk_add_f32 v[190:191], v[190:191], v[168:169] op_sel_hi:[1,0]
	v_pk_add_f32 v[192:193], v[192:193], v[168:169] op_sel_hi:[1,0]
	v_rcp_f32_e32 v186, v186
	v_rcp_f32_e32 v187, v187
	v_rcp_f32_e32 v188, v188
	v_rcp_f32_e32 v189, v189
	v_rcp_f32_e32 v190, v190
	v_rcp_f32_e32 v191, v191
	v_rcp_f32_e32 v192, v192
	v_rcp_f32_e32 v193, v193
	v_pk_mul_f32 v[22:23], v[22:23], v[186:187]
	v_pk_mul_f32 v[24:25], v[24:25], v[188:189]
	v_pk_mul_f32 v[18:19], v[18:19], v[190:191]
	v_pk_mul_f32 v[20:21], v[20:21], v[192:193]
	v_pk_mul_f32 v[30:31], v[30:31], v[22:23]
	v_pk_mul_f32 v[32:33], v[32:33], v[24:25]
	v_pk_mul_f32 v[26:27], v[26:27], v[18:19]
	v_pk_mul_f32 v[28:29], v[28:29], v[20:21]
	v_add_u32_e32 v194, 160, v140
	v_mad_i64_i32 v[194:195], s[42:43], v194, s31, v[196:197]
	v_lshl_add_u64 v[194:195], v[194:195], 0, v[198:199]
	v_cvt_pk_bf16_f32 v22, v30, v31
	v_cvt_pk_bf16_f32 v23, v32, v33
	v_cvt_pk_bf16_f32 v24, v26, v27
	v_cvt_pk_bf16_f32 v25, v28, v29
	global_store_dwordx4 v[194:195], v[22:25], off
	v_mov_b32_e32 v194, v161
	v_pk_mul_f32 v[14:15], v[14:15], v[194:195] op_sel_hi:[1,0]
	v_pk_mul_f32 v[16:17], v[16:17], v[194:195] op_sel_hi:[1,0]
	v_pk_mul_f32 v[6:7], v[6:7], v[194:195] op_sel_hi:[1,0]
	v_pk_mul_f32 v[8:9], v[8:9], v[194:195] op_sel_hi:[1,0]
	v_pk_mul_f32 v[10:11], v[10:11], v[194:195] op_sel_hi:[1,0]
	v_pk_mul_f32 v[12:13], v[12:13], v[194:195] op_sel_hi:[1,0]
	v_pk_mul_f32 v[2:3], v[2:3], v[194:195] op_sel_hi:[1,0]
	v_pk_mul_f32 v[4:5], v[4:5], v[194:195] op_sel_hi:[1,0]
	v_pk_mul_f32 v[186:187], v[14:15], v[170:171] op_sel_hi:[1,0]
	v_pk_mul_f32 v[188:189], v[16:17], v[170:171] op_sel_hi:[1,0]
	v_pk_mul_f32 v[190:191], v[6:7], v[170:171] op_sel_hi:[1,0]
	v_pk_mul_f32 v[192:193], v[8:9], v[170:171] op_sel_hi:[1,0]
	v_exp_f32_e32 v186, v186
	v_exp_f32_e32 v187, v187
	v_exp_f32_e32 v188, v188
	v_exp_f32_e32 v189, v189
	v_exp_f32_e32 v190, v190
	v_exp_f32_e32 v191, v191
	v_exp_f32_e32 v192, v192
	v_exp_f32_e32 v193, v193
	v_pk_add_f32 v[186:187], v[186:187], v[168:169] op_sel_hi:[1,0]
	v_pk_add_f32 v[188:189], v[188:189], v[168:169] op_sel_hi:[1,0]
	v_pk_add_f32 v[190:191], v[190:191], v[168:169] op_sel_hi:[1,0]
	v_pk_add_f32 v[192:193], v[192:193], v[168:169] op_sel_hi:[1,0]
	v_rcp_f32_e32 v186, v186
	v_rcp_f32_e32 v187, v187
	v_rcp_f32_e32 v188, v188
	v_rcp_f32_e32 v189, v189
	v_rcp_f32_e32 v190, v190
	v_rcp_f32_e32 v191, v191
	v_rcp_f32_e32 v192, v192
	v_rcp_f32_e32 v193, v193
	v_pk_mul_f32 v[14:15], v[14:15], v[186:187]
	v_pk_mul_f32 v[16:17], v[16:17], v[188:189]
	v_pk_mul_f32 v[6:7], v[6:7], v[190:191]
	v_pk_mul_f32 v[8:9], v[8:9], v[192:193]
	v_pk_mul_f32 v[10:11], v[10:11], v[14:15]
	v_pk_mul_f32 v[12:13], v[12:13], v[16:17]
	v_pk_mul_f32 v[2:3], v[2:3], v[6:7]
	v_pk_mul_f32 v[4:5], v[4:5], v[8:9]
	v_add_u32_e32 v194, 176, v140
	v_mad_i64_i32 v[194:195], s[42:43], v194, s31, v[196:197]
	v_lshl_add_u64 v[194:195], v[194:195], 0, v[198:199]
	v_cvt_pk_bf16_f32 v14, v10, v11
	v_cvt_pk_bf16_f32 v15, v12, v13
	v_cvt_pk_bf16_f32 v16, v2, v3
	v_cvt_pk_bf16_f32 v17, v4, v5
	global_store_dwordx4 v[194:195], v[14:17], off
	s_mov_b64 s[12:13], -1
	s_andn2_b64 vcc, exec, s[40:41]
	s_cbranch_vccnz .LBB0_20
	s_andn2_b64 vcc, exec, s[16:17]
	s_cbranch_vccnz .LBB0_19
	s_barrier
	s_branch .LBB0_19
